# cmp importance-table zero-init: 32-trip ds_write_b32 loop replaced by 8 straight-line ds_write_b128 per thread
# baseline (speedup 1.0000x reference)
; __device__ __forceinline__ void phase_cmp(const Params& p, LAS unsigned char* lds, const bf16_t* Z, const float* G, const bf16_t* KC, const bf16_t* ACCW, float* ACC, int* IDX, ...
;     ...
;         if (qb >= 16) {
;             __syncthreads();
;             for (int e = tid; e < 16384; e += 512) PS[e] = 0u;
.LBB0_392:
	s_andn2_b64 vcc, exec, s[20:21]
	s_cbranch_vccnz .LBB0_452
	s_barrier
	s_and_saveexec_b64 s[18:19], s[6:7]
	v_mad_u32_u24 v0, v74, 12, v137
	v_mov_b32_e32 v2, 0
	v_mov_b32_e32 v3, 0
	v_mov_b32_e32 v4, 0
	v_mov_b32_e32 v5, 0
	ds_write_b128 v0, v[2:5]
	ds_write_b128 v0, v[2:5] offset:8192
	ds_write_b128 v0, v[2:5] offset:16384
	ds_write_b128 v0, v[2:5] offset:24576
	ds_write_b128 v0, v[2:5] offset:32768
	ds_write_b128 v0, v[2:5] offset:40960
	ds_write_b128 v0, v[2:5] offset:49152
	ds_write_b128 v0, v[2:5] offset:57344
